# p4 h3: both 64-byte state slabs prefetched (slab 0 before the QK^T stage, slab 1 during slab 0) instead of load-then-wait at the point of use
# baseline (speedup 1.0000x reference)
; DEVI void h3_item(const Params& P, int l, int ck, int h, char* smem, int tid) {
;     ...
;   bf16x8 aq[4];
; #pragma unroll
;   for (int kk = 0; kk < 4; ++kk) aq[kk] = *reinterpret_cast<const bf16x8*>(QT + (16 * w + fr) * 136 + kk * 32 + fq * 8);
;   {
;     f32x4 sa[4];
; #pragma unroll
;     for (int n = 0; n < 4; ++n) sa[n] = f32x4{0.f, 0.f, 0.f, 0.f};
; #pragma unroll
;     for (int kk = 0; kk < 4; ++kk)
; #pragma unroll
;       for (int n = 0; n < 4; ++n) {
;         bf16x8 bk = *reinterpret_cast<const bf16x8*>(KT + (n * 16 + fr) * 136 + kk * 32 + fq * 8);
;         sa[n] = __builtin_amdgcn_mfma_f32_16x16x32_bf16(aq[kk], bk, sa[n], 0, 0, 0);
;       }
; #pragma unroll
;     for (int n = 0; n < 4; ++n)
; #pragma unroll
;       for (int j = 0; j < 4; ++j) {
;         int t = 16 * w + fq * 4 + j, s = n * 16 + fr;
;         AT[t * 72 + s] = (s <= t) ? f2b(sa[n][j]) : (bfu)0;
;       }
;   }
;     ...
;       const bfu* src = (const bfu*)(P.ws + O_US) + ((long)((ci.seqi * 8 + h) * 64 + ci.c) << 14);
;       int e2 = tid >> 1, dd0 = (tid & 1) * 32;
; #pragma unroll
;       for (int q4 = 0; q4 < 4; ++q4) {
;         uint4 v = *reinterpret_cast<const uint4*>(src + e2 * 128 + sl * 64 + dd0 + q4 * 8);
.LBB0_568:
	s_or_b64 exec, exec, s[74:75]
	s_and_b64 vcc, exec, s[26:27]
	s_cbranch_vccnz .Lh3_nopf
	s_lshl_b32 vcc_lo, s52, 9
	s_lshl_b32 vcc_hi, s54, 6
	s_or_b32 vcc_lo, vcc_lo, vcc_hi
	s_or_b32 vcc_lo, s53, vcc_lo
	s_ashr_i32 vcc_hi, vcc_lo, 31
	s_lshl_b64 vcc, vcc, 15
	v_lshl_add_u64 v[244:245], v[114:115], 0, vcc
	global_load_dwordx4 v[228:231], v[244:245], off offset:48
	global_load_dwordx4 v[232:235], v[244:245], off offset:32
	global_load_dwordx4 v[236:239], v[244:245], off offset:16
	global_load_dwordx4 v[240:243], v[244:245], off
.Lh3_nopf:
	s_waitcnt lgkmcnt(0)
	s_barrier
	ds_read_b128 v[12:15], v210
	ds_read_b128 v[8:11], v210 offset:64
	ds_read_b128 v[4:7], v210 offset:128
	ds_read_b128 v[0:3], v210 offset:192
	ds_read_b128 v[32:35], v211 offset:17408
	ds_read_b128 v[36:39], v211 offset:21760
	ds_read_b128 v[48:51], v211 offset:17472
	s_waitcnt lgkmcnt(2)
	v_mfma_f32_16x16x32_bf16 v[32:35], v[12:15], v[32:35], 0
	ds_read_b128 v[40:43], v211 offset:26112
	ds_read_b128 v[44:47], v211 offset:30464
	v_readlane_b32 s4, v252, 34
	s_waitcnt lgkmcnt(2)
	v_mfma_f32_16x16x32_bf16 v[32:35], v[8:11], v[48:51], v[32:35]
	ds_read_b128 v[48:51], v211 offset:21824
	v_readlane_b32 s5, v252, 35
	s_lshl_b32 s55, s52, 3
	v_mfma_f32_16x16x32_bf16 v[36:39], v[12:15], v[36:39], 0
	s_add_i32 s55, s55, s45
	s_or_b32 s56, s55, s54
	s_ashr_i32 s57, s56, 31
	s_waitcnt lgkmcnt(0)
	v_mfma_f32_16x16x32_bf16 v[36:39], v[8:11], v[48:51], v[36:39]
	ds_read_b128 v[48:51], v211 offset:26176
	s_lshl_b64 s[74:75], s[56:57], 16
	s_mov_b64 s[76:77], -1
	v_mfma_f32_16x16x32_bf16 v[40:43], v[12:15], v[40:43], 0
	s_and_b64 vcc, exec, s[26:27]
	s_waitcnt lgkmcnt(0)
	v_mfma_f32_16x16x32_bf16 v[40:43], v[8:11], v[48:51], v[40:43]
	ds_read_b128 v[48:51], v211 offset:30528
	v_mfma_f32_16x16x32_bf16 v[44:47], v[12:15], v[44:47], 0
	s_waitcnt lgkmcnt(0)
	v_mfma_f32_16x16x32_bf16 v[44:47], v[8:11], v[48:51], v[44:47]
	ds_read_b128 v[48:51], v211 offset:17536
	s_waitcnt lgkmcnt(0)
	v_mfma_f32_16x16x32_bf16 v[32:35], v[4:7], v[48:51], v[32:35]
	ds_read_b128 v[48:51], v211 offset:21888
	s_waitcnt lgkmcnt(0)
	v_mfma_f32_16x16x32_bf16 v[36:39], v[4:7], v[48:51], v[36:39]
	ds_read_b128 v[48:51], v211 offset:26240
	s_waitcnt lgkmcnt(0)
	v_mfma_f32_16x16x32_bf16 v[40:43], v[4:7], v[48:51], v[40:43]
	ds_read_b128 v[48:51], v211 offset:30592
	s_waitcnt lgkmcnt(0)
	v_mfma_f32_16x16x32_bf16 v[44:47], v[4:7], v[48:51], v[44:47]
	ds_read_b128 v[48:51], v211 offset:17600
	s_waitcnt lgkmcnt(0)
	v_mfma_f32_16x16x32_bf16 v[32:35], v[0:3], v[48:51], v[32:35]
	ds_read_b128 v[48:51], v211 offset:21952
	s_waitcnt lgkmcnt(0)
	v_mfma_f32_16x16x32_bf16 v[36:39], v[0:3], v[48:51], v[36:39]
	ds_read_b128 v[48:51], v211 offset:26304
	s_waitcnt lgkmcnt(0)
	v_mfma_f32_16x16x32_bf16 v[40:43], v[0:3], v[48:51], v[40:43]
	ds_read_b128 v[48:51], v211 offset:30656
	s_waitcnt lgkmcnt(0)
	v_mfma_f32_16x16x32_bf16 v[44:47], v[0:3], v[48:51], v[44:47]
	v_bfe_u32 v48, v32, 16, 1
	v_add3_u32 v32, v32, v48, s39
	v_lshrrev_b32_e32 v32, 16, v32
	v_cndmask_b32_e64 v32, v32, 0, s[4:5]
	ds_write_b16 v212, v32 offset:34816
	v_bfe_u32 v32, v33, 16, 1
	v_add3_u32 v32, v33, v32, s39
	v_readlane_b32 s4, v252, 39
	v_lshrrev_b32_e32 v32, 16, v32
	v_readlane_b32 s5, v252, 40
	s_nop 1
	v_cndmask_b32_e64 v32, v32, 0, s[4:5]
	ds_write_b16 v212, v32 offset:34960
	v_bfe_u32 v32, v34, 16, 1
	v_add3_u32 v32, v34, v32, s39
	v_readlane_b32 s4, v252, 41
	v_lshrrev_b32_e32 v32, 16, v32
	v_readlane_b32 s5, v252, 42
	s_nop 1
	v_cndmask_b32_e64 v32, v32, 0, s[4:5]
	ds_write_b16 v212, v32 offset:35104
	v_bfe_u32 v32, v35, 16, 1
	v_add3_u32 v32, v35, v32, s39
	v_readlane_b32 s4, v252, 43
	v_lshrrev_b32_e32 v32, 16, v32
	v_readlane_b32 s5, v252, 44
	s_nop 1
	v_cndmask_b32_e64 v32, v32, 0, s[4:5]
	ds_write_b16 v212, v32 offset:35248
	v_bfe_u32 v32, v36, 16, 1
	v_add3_u32 v32, v36, v32, s39
	v_readlane_b32 s4, v252, 45
	v_lshrrev_b32_e32 v32, 16, v32
	v_readlane_b32 s5, v252, 46
	s_nop 1
	v_cndmask_b32_e64 v32, v32, 0, s[4:5]
	ds_write_b16 v212, v32 offset:34848
	v_bfe_u32 v32, v37, 16, 1
	v_add3_u32 v32, v37, v32, s39
	v_readlane_b32 s4, v252, 47
	v_lshrrev_b32_e32 v32, 16, v32
	v_readlane_b32 s5, v252, 48
	s_nop 1
	v_cndmask_b32_e64 v32, v32, 0, s[4:5]
	ds_write_b16 v212, v32 offset:34992
	v_bfe_u32 v32, v38, 16, 1
	v_add3_u32 v32, v38, v32, s39
	v_readlane_b32 s4, v252, 49
	v_lshrrev_b32_e32 v32, 16, v32
	v_readlane_b32 s5, v252, 50
	s_nop 1
	v_cndmask_b32_e64 v32, v32, 0, s[4:5]
	ds_write_b16 v212, v32 offset:35136
	v_bfe_u32 v32, v39, 16, 1
	v_add3_u32 v32, v39, v32, s39
	v_readlane_b32 s4, v252, 51
	v_lshrrev_b32_e32 v32, 16, v32
	v_readlane_b32 s5, v252, 52
	s_nop 1
	v_cndmask_b32_e64 v32, v32, 0, s[4:5]
	ds_write_b16 v212, v32 offset:35280
	v_bfe_u32 v32, v40, 16, 1
	v_add3_u32 v32, v40, v32, s39
	v_readlane_b32 s4, v252, 53
	v_lshrrev_b32_e32 v32, 16, v32
	v_readlane_b32 s5, v252, 54
	s_nop 1
	v_cndmask_b32_e64 v32, v32, 0, s[4:5]
	ds_write_b16 v212, v32 offset:34880
	v_bfe_u32 v32, v41, 16, 1
	v_add3_u32 v32, v41, v32, s39
	v_readlane_b32 s4, v252, 55
	v_lshrrev_b32_e32 v32, 16, v32
	v_readlane_b32 s5, v252, 56
	s_nop 1
	v_cndmask_b32_e64 v32, v32, 0, s[4:5]
	ds_write_b16 v212, v32 offset:35024
	v_bfe_u32 v32, v42, 16, 1
	v_add3_u32 v32, v42, v32, s39
	v_readlane_b32 s4, v252, 57
	v_lshrrev_b32_e32 v32, 16, v32
	v_readlane_b32 s5, v252, 58
	s_nop 1
	v_cndmask_b32_e64 v32, v32, 0, s[4:5]
	ds_write_b16 v212, v32 offset:35168
	v_bfe_u32 v32, v43, 16, 1
	v_add3_u32 v32, v43, v32, s39
	v_lshrrev_b32_e32 v32, 16, v32
	v_cndmask_b32_e64 v32, v32, 0, s[64:65]
	ds_write_b16 v212, v32 offset:35312
	v_bfe_u32 v32, v44, 16, 1
	v_add3_u32 v32, v44, v32, s39
	v_lshrrev_b32_e32 v32, 16, v32
	v_cndmask_b32_e64 v32, v32, 0, s[66:67]
	ds_write_b16 v212, v32 offset:34912
	v_bfe_u32 v32, v45, 16, 1
	v_add3_u32 v32, v45, v32, s39
	v_lshrrev_b32_e32 v32, 16, v32
	v_cndmask_b32_e64 v32, v32, 0, s[40:41]
	ds_write_b16 v212, v32 offset:35056
	v_bfe_u32 v32, v46, 16, 1
	v_add3_u32 v32, v46, v32, s39
	v_lshrrev_b32_e32 v32, 16, v32
	v_cndmask_b32_e64 v32, v32, 0, s[42:43]
	ds_write_b16 v212, v32 offset:35200
	v_bfe_u32 v32, v47, 16, 1
	v_add3_u32 v32, v47, v32, s39
	v_lshrrev_b32_e32 v32, 16, v32
	v_cndmask_b32_e64 v32, v32, 0, s[62:63]
	ds_write_b16 v212, v32 offset:35344
	s_waitcnt lgkmcnt(0)
	s_barrier
; DEVI void h3_item(const Params& P, int l, int ck, int h, char* smem, int tid) {
;     ...
;   __syncthreads();
; #pragma unroll
;   for (int q = 0; q < 4; ++q) {
;     const int idx = tid + 256 * q;
;     const int sr = (idx & 15) | (((idx >> 8) & 3) << 4), c16 = ((idx >> 4) & 3) | (((idx >> 6) & 3) << 2);
;     *reinterpret_cast<uint4*>(QT + sr * 136 + c16 * 8) = vg[q];
;   }
;   f32x4 o[8];
; #pragma unroll
;   for (int n = 0; n < 8; ++n) o[n] = f32x4{0.f, 0.f, 0.f, 0.f};
; #pragma unroll
;   for (int kk = 0; kk < 2; ++kk) {
;     bf16x8 a = *reinterpret_cast<const bf16x8*>(AT + (16 * w + fr) * 72 + kk * 32 + fq * 8);
; #pragma unroll
;     for (int n = 0; n < 8; ++n) {
;       bf16x8 b = *reinterpret_cast<const bf16x8*>(BS + (n * 16 + fr) * 72 + kk * 32 + fq * 8);
;       o[n] = __builtin_amdgcn_mfma_f32_16x16x32_bf16(a, b, o[n], 0, 0, 0);
;     }
;   }
; #pragma unroll
;   for (int sl = 0; sl < 2; ++sl) {
;     __syncthreads();
;     if (!ci.sample) {
	s_waitcnt vmcnt(0)
	ds_write_b128 v213, v[20:23]
	ds_write_b128 v214, v[16:19]
	ds_write_b128 v215, v[28:31]
	ds_write_b128 v216, v[24:27]
	ds_read_b128 v[16:19], v110 offset:34816
	ds_read_b128 v[20:23], v217 offset:44032
	ds_read_b128 v[24:27], v217 offset:46336
	ds_read_b128 v[28:31], v217 offset:48640
	ds_read_b128 v[32:35], v217 offset:50944
	ds_read_b128 v[36:39], v217 offset:53248
	ds_read_b128 v[40:43], v217 offset:55552
	ds_read_b128 v[44:47], v217 offset:57856
	ds_read_b128 v[48:51], v217 offset:60160
	s_waitcnt lgkmcnt(7)
	v_mfma_f32_16x16x32_bf16 v[20:23], v[16:19], v[20:23], 0
	s_waitcnt lgkmcnt(6)
	v_mfma_f32_16x16x32_bf16 v[24:27], v[16:19], v[24:27], 0
	s_waitcnt lgkmcnt(5)
	v_mfma_f32_16x16x32_bf16 v[28:31], v[16:19], v[28:31], 0
	s_waitcnt lgkmcnt(4)
	v_mfma_f32_16x16x32_bf16 v[32:35], v[16:19], v[32:35], 0
	s_waitcnt lgkmcnt(3)
	v_mfma_f32_16x16x32_bf16 v[36:39], v[16:19], v[36:39], 0
	s_waitcnt lgkmcnt(2)
	v_mfma_f32_16x16x32_bf16 v[40:43], v[16:19], v[40:43], 0
	s_waitcnt lgkmcnt(1)
	v_mfma_f32_16x16x32_bf16 v[44:47], v[16:19], v[44:47], 0
	s_waitcnt lgkmcnt(0)
	v_mfma_f32_16x16x32_bf16 v[48:51], v[16:19], v[48:51], 0
	ds_read_b128 v[52:55], v110 offset:34880
	ds_read_b128 v[16:19], v217 offset:44096
	s_waitcnt lgkmcnt(0)
	v_mfma_f32_16x16x32_bf16 v[16:19], v[52:55], v[16:19], v[20:23]
	s_nop 2
	ds_read_b128 v[20:23], v217 offset:46400
	s_waitcnt lgkmcnt(0)
	v_mfma_f32_16x16x32_bf16 v[20:23], v[52:55], v[20:23], v[24:27]
	s_nop 2
	ds_read_b128 v[24:27], v217 offset:48704
	s_waitcnt lgkmcnt(0)
	v_mfma_f32_16x16x32_bf16 v[24:27], v[52:55], v[24:27], v[28:31]
	s_nop 2
	ds_read_b128 v[28:31], v217 offset:51008
	s_waitcnt lgkmcnt(0)
	v_mfma_f32_16x16x32_bf16 v[28:31], v[52:55], v[28:31], v[32:35]
	s_nop 2
	ds_read_b128 v[32:35], v217 offset:53312
	s_waitcnt lgkmcnt(0)
	v_mfma_f32_16x16x32_bf16 v[32:35], v[52:55], v[32:35], v[36:39]
	s_nop 2
	ds_read_b128 v[36:39], v217 offset:55616
	s_waitcnt lgkmcnt(0)
	v_mfma_f32_16x16x32_bf16 v[36:39], v[52:55], v[36:39], v[40:43]
	s_nop 2
	ds_read_b128 v[40:43], v217 offset:57920
	s_waitcnt lgkmcnt(0)
	v_mfma_f32_16x16x32_bf16 v[40:43], v[52:55], v[40:43], v[44:47]
	s_nop 2
	ds_read_b128 v[44:47], v217 offset:60224
	s_waitcnt lgkmcnt(0)
	v_mfma_f32_16x16x32_bf16 v[44:47], v[52:55], v[44:47], v[48:51]
	s_barrier
	s_cbranch_vccz .LBB0_572
	v_readlane_b32 s4, v254, 44
	v_readlane_b32 s10, v254, 50
	v_readlane_b32 s11, v254, 51
	s_add_u32 s26, s10, s74
	s_addc_u32 s27, s11, s75
	s_mov_b32 s55, 0
	v_mov_b32_e32 v48, v207
	v_mov_b32_e32 v49, v206
	s_mov_b32 s4, 0x7060302
	v_readlane_b32 s5, v254, 45
	v_readlane_b32 s6, v254, 46
	v_readlane_b32 s7, v254, 47
	v_readlane_b32 s8, v254, 48
	v_readlane_b32 s9, v254, 49
	v_readlane_b32 s12, v254, 52
	v_readlane_b32 s13, v254, 53
	v_readlane_b32 s14, v254, 54
	v_readlane_b32 s15, v254, 55
	v_readlane_b32 s16, v254, 56
	v_readlane_b32 s17, v254, 57
	v_readlane_b32 s18, v254, 58
	v_readlane_b32 s19, v254, 59

; DEVI void h3_item(const Params& P, int l, int ck, int h, char* smem, int tid) {
;     ...
;     if (!ci.sample) {
;       const bfu* src = (const bfu*)(P.ws + O_US) + ((long)((ci.seqi * 8 + h) * 64 + ci.c) << 14);
;       int e2 = tid >> 1, dd0 = (tid & 1) * 32;
; #pragma unroll
;       for (int q4 = 0; q4 < 4; ++q4) {
;         uint4 v = *reinterpret_cast<const uint4*>(src + e2 * 128 + sl * 64 + dd0 + q4 * 8);
;         const float* bm = bmid + sl * 64 + dd0 + q4 * 8;
;         unsigned vv[4] = {v.x, v.y, v.z, v.w};
;         unsigned rr[4];
; #pragma unroll
;         for (int i = 0; i < 4; ++i) {
;           float lo = __uint_as_float(vv[i] << 16) * __expf(bm[2 * i]);
;           float hi = __uint_as_float(vv[i] & 0xFFFF0000u) * __expf(bm[2 * i + 1]);
;           rr[i] = f2b(lo) | ((unsigned)f2b(hi) << 16);
;         }
;         *reinterpret_cast<uint4*>(BS + e2 * 72 + dd0 + q4 * 8) = make_uint4(rr[0], rr[1], rr[2], rr[3]);
;       }
.LBB0_572:
	s_lshl_b32 s26, s52, 9
	s_lshl_b32 s27, s54, 6
	s_or_b32 s26, s26, s27
	s_or_b32 s26, s53, s26
	s_ashr_i32 s27, s26, 31
	s_lshl_b64 s[26:27], s[26:27], 15
	s_and_b64 vcc, exec, s[76:77]
	s_cbranch_vccz .LBB0_574
	ds_read_b128 v[48:51], v111 offset:62464
	ds_read_b128 v[52:55], v111 offset:62480
	v_lshl_add_u64 v[60:61], v[114:115], 0, s[26:27]
	s_waitcnt lgkmcnt(1)
	v_mul_f32_e32 v48, 0x3fb8aa3b, v48
	v_exp_f32_e32 v148, v48
	v_mul_f32_e32 v48, 0x3fb8aa3b, v49
	v_exp_f32_e32 v150, v48
	v_mul_f32_e32 v48, 0x3fb8aa3b, v50
	v_exp_f32_e32 v149, v48
	v_mul_f32_e32 v48, 0x3fb8aa3b, v51
	v_exp_f32_e32 v151, v48
	s_waitcnt lgkmcnt(0)
	v_mul_f32_e32 v48, 0x3fb8aa3b, v52
	v_exp_f32_e32 v152, v48
	v_mul_f32_e32 v48, 0x3fb8aa3b, v53
	v_exp_f32_e32 v154, v48
	v_mul_f32_e32 v48, 0x3fb8aa3b, v54
	v_exp_f32_e32 v153, v48
	v_mul_f32_e32 v48, 0x3fb8aa3b, v55
	v_exp_f32_e32 v155, v48
	s_waitcnt vmcnt(0)
	v_mov_b32_e32 v48, v228
	v_mov_b32_e32 v49, v229
	v_mov_b32_e32 v50, v230
	v_mov_b32_e32 v51, v231
	v_mov_b32_e32 v52, v232
	v_mov_b32_e32 v53, v233
	v_mov_b32_e32 v54, v234
	v_mov_b32_e32 v55, v235
	v_mov_b32_e32 v56, v236
	v_mov_b32_e32 v57, v237
	v_mov_b32_e32 v58, v238
	v_mov_b32_e32 v59, v239
	v_mov_b32_e32 v60, v240
	v_mov_b32_e32 v61, v241
	v_mov_b32_e32 v62, v242
	v_mov_b32_e32 v63, v243
	v_lshl_add_u64 v[244:245], v[116:117], 0, s[26:27]
	v_mov_b32_e32 v147, v89
	s_mov_b64 vcc, 0x1d006080
	v_lshl_add_u64 v[244:245], v[244:245], 0, v[146:147]
	v_lshl_add_u64 v[244:245], v[244:245], 0, vcc
	global_load_dwordx4 v[228:231], v[244:245], off
	global_load_dwordx4 v[232:235], v[244:245], off offset:48
	global_load_dwordx4 v[236:239], v[244:245], off offset:32
	global_load_dwordx4 v[240:243], v[244:245], off offset:16
	v_lshlrev_b32_e32 v157, 16, v61
	v_lshlrev_b32_e32 v156, 16, v60
	v_pk_mul_f32 v[148:149], v[148:149], v[156:157]
	v_and_b32_e32 v61, 0xffff0000, v61
	v_and_b32_e32 v60, 0xffff0000, v60
	v_pk_mul_f32 v[60:61], v[150:151], v[60:61]
	v_and_b32_sdwa v88, v149, v95 dst_sel:DWORD dst_unused:UNUSED_PAD src0_sel:WORD_1 src1_sel:DWORD
	v_and_b32_sdwa v133, v148, v95 dst_sel:DWORD dst_unused:UNUSED_PAD src0_sel:WORD_1 src1_sel:DWORD
	v_add3_u32 v133, v148, v133, s39
	v_add3_u32 v88, v149, v88, s39
	v_and_b32_sdwa v137, v61, v95 dst_sel:DWORD dst_unused:UNUSED_PAD src0_sel:WORD_1 src1_sel:DWORD
	v_and_b32_sdwa v141, v60, v95 dst_sel:DWORD dst_unused:UNUSED_PAD src0_sel:WORD_1 src1_sel:DWORD
	v_lshlrev_b32_e32 v149, 16, v63
	v_lshlrev_b32_e32 v148, 16, v62
	v_and_b32_e32 v63, 0xffff0000, v63
	v_and_b32_e32 v62, 0xffff0000, v62
	v_add3_u32 v61, v61, v137, s39
	v_add3_u32 v60, v60, v141, s39
	v_pk_mul_f32 v[62:63], v[154:155], v[62:63]
	v_and_b32_e32 v61, 0xffff0000, v61
	v_and_b32_e32 v60, 0xffff0000, v60
	v_pk_mul_f32 v[148:149], v[152:153], v[148:149]
	v_and_b32_sdwa v137, v63, v95 dst_sel:DWORD dst_unused:UNUSED_PAD src0_sel:WORD_1 src1_sel:DWORD
	v_and_b32_sdwa v141, v62, v95 dst_sel:DWORD dst_unused:UNUSED_PAD src0_sel:WORD_1 src1_sel:DWORD
	v_or_b32_sdwa v61, v61, v88 dst_sel:DWORD dst_unused:UNUSED_PAD src0_sel:DWORD src1_sel:WORD_1
	v_or_b32_sdwa v60, v60, v133 dst_sel:DWORD dst_unused:UNUSED_PAD src0_sel:DWORD src1_sel:WORD_1
	v_and_b32_sdwa v88, v149, v95 dst_sel:DWORD dst_unused:UNUSED_PAD src0_sel:WORD_1 src1_sel:DWORD
	v_and_b32_sdwa v133, v148, v95 dst_sel:DWORD dst_unused:UNUSED_PAD src0_sel:WORD_1 src1_sel:DWORD
	v_add3_u32 v63, v63, v137, s39
	v_add3_u32 v62, v62, v141, s39
	v_add3_u32 v133, v148, v133, s39
	v_add3_u32 v88, v149, v88, s39
	v_and_b32_e32 v63, 0xffff0000, v63
	v_and_b32_e32 v62, 0xffff0000, v62
	v_or_b32_sdwa v63, v63, v88 dst_sel:DWORD dst_unused:UNUSED_PAD src0_sel:DWORD src1_sel:WORD_1
	v_or_b32_sdwa v62, v62, v133 dst_sel:DWORD dst_unused:UNUSED_PAD src0_sel:DWORD src1_sel:WORD_1
	ds_write_b128 v112, v[60:63] offset:44032
	ds_read_b128 v[60:63], v111 offset:62496
	ds_read_b128 v[148:151], v111 offset:62512
	s_waitcnt lgkmcnt(1)
	v_mul_f32_e32 v60, 0x3fb8aa3b, v60
	v_exp_f32_e32 v152, v60
	v_mul_f32_e32 v60, 0x3fb8aa3b, v61
	v_exp_f32_e32 v154, v60
	v_mul_f32_e32 v60, 0x3fb8aa3b, v62
	v_exp_f32_e32 v153, v60
	v_mul_f32_e32 v60, 0x3fb8aa3b, v63
	v_exp_f32_e32 v155, v60
	s_waitcnt lgkmcnt(0)
	v_mul_f32_e32 v60, 0x3fb8aa3b, v148
	v_mul_f32_e32 v61, 0x3fb8aa3b, v150
	v_exp_f32_e32 v62, v60
	v_mul_f32_e32 v60, 0x3fb8aa3b, v149
	v_exp_f32_e32 v63, v61
	v_mul_f32_e32 v61, 0x3fb8aa3b, v151
	v_lshlrev_b32_e32 v149, 16, v57
	v_lshlrev_b32_e32 v148, 16, v56
	v_exp_f32_e32 v60, v60
	v_exp_f32_e32 v61, v61
	v_pk_mul_f32 v[148:149], v[152:153], v[148:149]
	v_and_b32_e32 v57, 0xffff0000, v57
	v_and_b32_sdwa v88, v149, v95 dst_sel:DWORD dst_unused:UNUSED_PAD src0_sel:WORD_1 src1_sel:DWORD
	v_and_b32_sdwa v133, v148, v95 dst_sel:DWORD dst_unused:UNUSED_PAD src0_sel:WORD_1 src1_sel:DWORD
	v_add3_u32 v133, v148, v133, s39
	v_add3_u32 v88, v149, v88, s39
	v_lshlrev_b32_e32 v149, 16, v59
	v_lshlrev_b32_e32 v148, 16, v58
	v_and_b32_e32 v56, 0xffff0000, v56
	v_pk_mul_f32 v[62:63], v[62:63], v[148:149]
	v_and_b32_e32 v59, 0xffff0000, v59
	v_and_b32_e32 v58, 0xffff0000, v58
	v_pk_mul_f32 v[56:57], v[154:155], v[56:57]
	v_pk_mul_f32 v[58:59], v[60:61], v[58:59]
	v_and_b32_sdwa v60, v63, v95 dst_sel:DWORD dst_unused:UNUSED_PAD src0_sel:WORD_1 src1_sel:DWORD
	v_and_b32_sdwa v61, v62, v95 dst_sel:DWORD dst_unused:UNUSED_PAD src0_sel:WORD_1 src1_sel:DWORD
	v_and_b32_sdwa v137, v57, v95 dst_sel:DWORD dst_unused:UNUSED_PAD src0_sel:WORD_1 src1_sel:DWORD
	v_and_b32_sdwa v141, v56, v95 dst_sel:DWORD dst_unused:UNUSED_PAD src0_sel:WORD_1 src1_sel:DWORD
	v_add3_u32 v61, v62, v61, s39
	v_add3_u32 v60, v63, v60, s39
	v_and_b32_sdwa v62, v59, v95 dst_sel:DWORD dst_unused:UNUSED_PAD src0_sel:WORD_1 src1_sel:DWORD
	v_and_b32_sdwa v63, v58, v95 dst_sel:DWORD dst_unused:UNUSED_PAD src0_sel:WORD_1 src1_sel:DWORD
	v_add3_u32 v57, v57, v137, s39
	v_add3_u32 v56, v56, v141, s39
	v_add3_u32 v59, v59, v62, s39
	v_add3_u32 v58, v58, v63, s39
	v_and_b32_e32 v57, 0xffff0000, v57
	v_and_b32_e32 v56, 0xffff0000, v56
	v_and_b32_e32 v59, 0xffff0000, v59
	v_and_b32_e32 v58, 0xffff0000, v58
	v_or_b32_sdwa v57, v57, v88 dst_sel:DWORD dst_unused:UNUSED_PAD src0_sel:DWORD src1_sel:WORD_1
	v_or_b32_sdwa v56, v56, v133 dst_sel:DWORD dst_unused:UNUSED_PAD src0_sel:DWORD src1_sel:WORD_1
	v_or_b32_sdwa v59, v59, v60 dst_sel:DWORD dst_unused:UNUSED_PAD src0_sel:DWORD src1_sel:WORD_1
	v_or_b32_sdwa v58, v58, v61 dst_sel:DWORD dst_unused:UNUSED_PAD src0_sel:DWORD src1_sel:WORD_1
	ds_write_b128 v112, v[56:59] offset:44048
	ds_read_b128 v[56:59], v111 offset:62528
	ds_read_b128 v[60:63], v111 offset:62544
	s_waitcnt lgkmcnt(1)
; DEVI void h3_item(const Params& P, int l, int ck, int h, char* smem, int tid) {
;     ...
; #pragma unroll
;       for (int q4 = 0; q4 < 4; ++q4) {
;         uint4 v = *reinterpret_cast<const uint4*>(src + e2 * 128 + sl * 64 + dd0 + q4 * 8);
;         const float* bm = bmid + sl * 64 + dd0 + q4 * 8;
;         unsigned vv[4] = {v.x, v.y, v.z, v.w};
;         unsigned rr[4];
; #pragma unroll
;         for (int i = 0; i < 4; ++i) {
;           float lo = __uint_as_float(vv[i] << 16) * __expf(bm[2 * i]);
;           float hi = __uint_as_float(vv[i] & 0xFFFF0000u) * __expf(bm[2 * i + 1]);
;           rr[i] = f2b(lo) | ((unsigned)f2b(hi) << 16);
;         }
;         *reinterpret_cast<uint4*>(BS + e2 * 72 + dd0 + q4 * 8) = make_uint4(rr[0], rr[1], rr[2], rr[3]);
;       }
	v_mul_f32_e32 v57, 0x3fb8aa3b, v57
	v_mul_f32_e32 v56, 0x3fb8aa3b, v56
	v_exp_f32_e32 v148, v57
	v_mul_f32_e32 v57, 0x3fb8aa3b, v58
	v_exp_f32_e32 v56, v56
	v_exp_f32_e32 v57, v57
	v_mul_f32_e32 v58, 0x3fb8aa3b, v59
	v_exp_f32_e32 v149, v58
	s_waitcnt lgkmcnt(0)
	v_mul_f32_e32 v59, 0x3fb8aa3b, v61
	v_mul_f32_e32 v58, 0x3fb8aa3b, v60
	v_exp_f32_e32 v60, v59
	v_mul_f32_e32 v59, 0x3fb8aa3b, v62
	v_mul_f32_e32 v61, 0x3fb8aa3b, v63
	v_lshlrev_b32_e32 v63, 16, v53
	v_lshlrev_b32_e32 v62, 16, v52
	v_pk_mul_f32 v[56:57], v[56:57], v[62:63]
	v_and_b32_e32 v53, 0xffff0000, v53
	v_and_b32_e32 v52, 0xffff0000, v52
	v_pk_mul_f32 v[52:53], v[148:149], v[52:53]
	v_and_b32_sdwa v62, v57, v95 dst_sel:DWORD dst_unused:UNUSED_PAD src0_sel:WORD_1 src1_sel:DWORD
	v_and_b32_sdwa v63, v56, v95 dst_sel:DWORD dst_unused:UNUSED_PAD src0_sel:WORD_1 src1_sel:DWORD
	v_exp_f32_e32 v58, v58
	v_exp_f32_e32 v59, v59
	v_add3_u32 v56, v56, v63, s39
	v_add3_u32 v57, v57, v62, s39
	v_and_b32_sdwa v62, v53, v95 dst_sel:DWORD dst_unused:UNUSED_PAD src0_sel:WORD_1 src1_sel:DWORD
	v_and_b32_sdwa v63, v52, v95 dst_sel:DWORD dst_unused:UNUSED_PAD src0_sel:WORD_1 src1_sel:DWORD
	v_exp_f32_e32 v61, v61
	v_add3_u32 v53, v53, v62, s39
	v_add3_u32 v52, v52, v63, s39
	v_and_b32_e32 v53, 0xffff0000, v53
	v_and_b32_e32 v52, 0xffff0000, v52
	v_or_b32_sdwa v53, v53, v57 dst_sel:DWORD dst_unused:UNUSED_PAD src0_sel:DWORD src1_sel:WORD_1
	v_or_b32_sdwa v52, v52, v56 dst_sel:DWORD dst_unused:UNUSED_PAD src0_sel:DWORD src1_sel:WORD_1
	v_lshlrev_b32_e32 v57, 16, v55
	v_lshlrev_b32_e32 v56, 16, v54
	v_pk_mul_f32 v[56:57], v[58:59], v[56:57]
	v_and_b32_e32 v55, 0xffff0000, v55
	v_and_b32_e32 v54, 0xffff0000, v54
	v_pk_mul_f32 v[54:55], v[60:61], v[54:55]
	v_and_b32_sdwa v58, v57, v95 dst_sel:DWORD dst_unused:UNUSED_PAD src0_sel:WORD_1 src1_sel:DWORD
	v_and_b32_sdwa v59, v56, v95 dst_sel:DWORD dst_unused:UNUSED_PAD src0_sel:WORD_1 src1_sel:DWORD
	v_add3_u32 v56, v56, v59, s39
	v_add3_u32 v57, v57, v58, s39
	v_and_b32_sdwa v58, v55, v95 dst_sel:DWORD dst_unused:UNUSED_PAD src0_sel:WORD_1 src1_sel:DWORD
	v_and_b32_sdwa v59, v54, v95 dst_sel:DWORD dst_unused:UNUSED_PAD src0_sel:WORD_1 src1_sel:DWORD
	v_add3_u32 v55, v55, v58, s39
	v_add3_u32 v54, v54, v59, s39
	v_and_b32_e32 v55, 0xffff0000, v55
	v_and_b32_e32 v54, 0xffff0000, v54
	v_or_b32_sdwa v55, v55, v57 dst_sel:DWORD dst_unused:UNUSED_PAD src0_sel:DWORD src1_sel:WORD_1
	v_or_b32_sdwa v54, v54, v56 dst_sel:DWORD dst_unused:UNUSED_PAD src0_sel:DWORD src1_sel:WORD_1
	ds_write_b128 v112, v[52:55] offset:44064
	ds_read_b128 v[52:55], v111 offset:62560
	ds_read_b128 v[56:59], v111 offset:62576
	s_waitcnt lgkmcnt(1)
	v_mul_f32_e32 v53, 0x3fb8aa3b, v53
	v_mul_f32_e32 v52, 0x3fb8aa3b, v52
	v_exp_f32_e32 v60, v53
	v_mul_f32_e32 v53, 0x3fb8aa3b, v54
	v_exp_f32_e32 v52, v52
	v_exp_f32_e32 v53, v53
	v_mul_f32_e32 v54, 0x3fb8aa3b, v55
	v_exp_f32_e32 v61, v54
	s_waitcnt lgkmcnt(0)
	v_mul_f32_e32 v55, 0x3fb8aa3b, v57
	v_mul_f32_e32 v54, 0x3fb8aa3b, v56
	v_exp_f32_e32 v56, v55
	v_mul_f32_e32 v55, 0x3fb8aa3b, v58
	v_mul_f32_e32 v57, 0x3fb8aa3b, v59
	v_lshlrev_b32_e32 v59, 16, v49
	v_lshlrev_b32_e32 v58, 16, v48
	v_pk_mul_f32 v[52:53], v[52:53], v[58:59]
	v_and_b32_e32 v49, 0xffff0000, v49
	v_and_b32_e32 v48, 0xffff0000, v48
	v_pk_mul_f32 v[48:49], v[60:61], v[48:49]
	v_and_b32_sdwa v58, v53, v95 dst_sel:DWORD dst_unused:UNUSED_PAD src0_sel:WORD_1 src1_sel:DWORD
	v_and_b32_sdwa v59, v52, v95 dst_sel:DWORD dst_unused:UNUSED_PAD src0_sel:WORD_1 src1_sel:DWORD
	v_exp_f32_e32 v54, v54
	v_exp_f32_e32 v55, v55
	v_add3_u32 v52, v52, v59, s39
	v_add3_u32 v53, v53, v58, s39
	v_and_b32_sdwa v58, v49, v95 dst_sel:DWORD dst_unused:UNUSED_PAD src0_sel:WORD_1 src1_sel:DWORD
	v_and_b32_sdwa v59, v48, v95 dst_sel:DWORD dst_unused:UNUSED_PAD src0_sel:WORD_1 src1_sel:DWORD
	v_exp_f32_e32 v57, v57
	v_add3_u32 v49, v49, v58, s39
	v_add3_u32 v48, v48, v59, s39
	v_and_b32_e32 v49, 0xffff0000, v49
	v_and_b32_e32 v48, 0xffff0000, v48
	v_or_b32_sdwa v49, v49, v53 dst_sel:DWORD dst_unused:UNUSED_PAD src0_sel:DWORD src1_sel:WORD_1
	v_or_b32_sdwa v48, v48, v52 dst_sel:DWORD dst_unused:UNUSED_PAD src0_sel:DWORD src1_sel:WORD_1
	v_lshlrev_b32_e32 v53, 16, v51
	v_lshlrev_b32_e32 v52, 16, v50
	v_pk_mul_f32 v[52:53], v[54:55], v[52:53]
	v_and_b32_e32 v51, 0xffff0000, v51
	v_and_b32_e32 v50, 0xffff0000, v50
	v_pk_mul_f32 v[50:51], v[56:57], v[50:51]
	v_and_b32_sdwa v54, v53, v95 dst_sel:DWORD dst_unused:UNUSED_PAD src0_sel:WORD_1 src1_sel:DWORD
	v_and_b32_sdwa v55, v52, v95 dst_sel:DWORD dst_unused:UNUSED_PAD src0_sel:WORD_1 src1_sel:DWORD
	v_add3_u32 v52, v52, v55, s39
	v_add3_u32 v53, v53, v54, s39
	v_and_b32_sdwa v54, v51, v95 dst_sel:DWORD dst_unused:UNUSED_PAD src0_sel:WORD_1 src1_sel:DWORD
	v_and_b32_sdwa v55, v50, v95 dst_sel:DWORD dst_unused:UNUSED_PAD src0_sel:WORD_1 src1_sel:DWORD
	v_add3_u32 v51, v51, v54, s39
	v_add3_u32 v50, v50, v55, s39
	v_and_b32_e32 v51, 0xffff0000, v51
	v_and_b32_e32 v50, 0xffff0000, v50
	v_or_b32_sdwa v51, v51, v53 dst_sel:DWORD dst_unused:UNUSED_PAD src0_sel:DWORD src1_sel:WORD_1
	v_or_b32_sdwa v50, v50, v52 dst_sel:DWORD dst_unused:UNUSED_PAD src0_sel:DWORD src1_sel:WORD_1
	ds_write_b128 v112, v[48:51] offset:44080

; DEVI void h3_item(const Params& P, int l, int ck, int h, char* smem, int tid) {
;     ...
;   for (int sl = 0; sl < 2; ++sl) {
;     __syncthreads();
;     if (!ci.sample) {
;       const bfu* src = (const bfu*)(P.ws + O_US) + ((long)((ci.seqi * 8 + h) * 64 + ci.c) << 14);
;       int e2 = tid >> 1, dd0 = (tid & 1) * 32;
; #pragma unroll
;       for (int q4 = 0; q4 < 4; ++q4) {
;         uint4 v = *reinterpret_cast<const uint4*>(src + e2 * 128 + sl * 64 + dd0 + q4 * 8);
;         const float* bm = bmid + sl * 64 + dd0 + q4 * 8;
;         unsigned vv[4] = {v.x, v.y, v.z, v.w};
;         unsigned rr[4];
; #pragma unroll
;         for (int i = 0; i < 4; ++i) {
;           float lo = __uint_as_float(vv[i] << 16) * __expf(bm[2 * i]);
;           float hi = __uint_as_float(vv[i] & 0xFFFF0000u) * __expf(bm[2 * i + 1]);
;           rr[i] = f2b(lo) | ((unsigned)f2b(hi) << 16);
;         }
;         *reinterpret_cast<uint4*>(BS + e2 * 72 + dd0 + q4 * 8) = make_uint4(rr[0], rr[1], rr[2], rr[3]);
;       }
.LBB0_578:
	s_and_b64 vcc, exec, s[76:77]
	s_cbranch_vccz .LBB0_580
	v_lshl_add_u64 v[40:41], v[116:117], 0, s[26:27]
	v_mov_b32_e32 v147, v89
	v_lshl_add_u64 v[48:49], v[40:41], 0, v[146:147]
	ds_read_b128 v[40:43], v111 offset:62720
	ds_read_b128 v[44:47], v111 offset:62736
	s_mov_b64 s[26:27], 0x1d006080
	v_lshl_add_u64 v[50:51], v[48:49], 0, s[26:27]
	s_mov_b32 s26, 0x1d006000
	s_waitcnt lgkmcnt(1)
	v_mul_f32_e32 v40, 0x3fb8aa3b, v40
	v_exp_f32_e32 v56, v40
	v_mul_f32_e32 v40, 0x3fb8aa3b, v41
	v_exp_f32_e32 v58, v40
	v_mul_f32_e32 v40, 0x3fb8aa3b, v42
	v_exp_f32_e32 v57, v40
	v_mul_f32_e32 v40, 0x3fb8aa3b, v43
	v_exp_f32_e32 v59, v40
	s_waitcnt lgkmcnt(0)
	v_mul_f32_e32 v40, 0x3fb8aa3b, v44
	v_exp_f32_e32 v60, v40
	v_mul_f32_e32 v40, 0x3fb8aa3b, v45
	v_exp_f32_e32 v62, v40
	v_mul_f32_e32 v40, 0x3fb8aa3b, v46
	v_exp_f32_e32 v61, v40
	v_mul_f32_e32 v40, 0x3fb8aa3b, v47
	v_exp_f32_e32 v63, v40
	s_waitcnt vmcnt(0)
	v_mov_b32_e32 v52, v228
	v_mov_b32_e32 v53, v229
	v_mov_b32_e32 v54, v230
	v_mov_b32_e32 v55, v231
	v_mov_b32_e32 v40, v232
	v_mov_b32_e32 v41, v233
	v_mov_b32_e32 v42, v234
	v_mov_b32_e32 v43, v235
	v_mov_b32_e32 v44, v236
	v_mov_b32_e32 v45, v237
	v_mov_b32_e32 v46, v238
	v_mov_b32_e32 v47, v239
	v_mov_b32_e32 v48, v240
	v_mov_b32_e32 v49, v241
	v_mov_b32_e32 v50, v242
	v_mov_b32_e32 v51, v243
	v_lshlrev_b32_e32 v149, 16, v53
	v_lshlrev_b32_e32 v148, 16, v52
	v_pk_mul_f32 v[56:57], v[56:57], v[148:149]
	v_and_b32_e32 v53, 0xffff0000, v53
	v_and_b32_e32 v52, 0xffff0000, v52
	v_pk_mul_f32 v[52:53], v[58:59], v[52:53]
	v_and_b32_sdwa v58, v57, v95 dst_sel:DWORD dst_unused:UNUSED_PAD src0_sel:WORD_1 src1_sel:DWORD
	v_and_b32_sdwa v59, v56, v95 dst_sel:DWORD dst_unused:UNUSED_PAD src0_sel:WORD_1 src1_sel:DWORD
	v_add3_u32 v56, v56, v59, s39
	v_add3_u32 v57, v57, v58, s39
	v_and_b32_sdwa v58, v53, v95 dst_sel:DWORD dst_unused:UNUSED_PAD src0_sel:WORD_1 src1_sel:DWORD
	v_and_b32_sdwa v59, v52, v95 dst_sel:DWORD dst_unused:UNUSED_PAD src0_sel:WORD_1 src1_sel:DWORD
	v_add3_u32 v53, v53, v58, s39
	v_add3_u32 v52, v52, v59, s39
	v_and_b32_e32 v53, 0xffff0000, v53
	v_and_b32_e32 v52, 0xffff0000, v52
	v_or_b32_sdwa v53, v53, v57 dst_sel:DWORD dst_unused:UNUSED_PAD src0_sel:DWORD src1_sel:WORD_1
	v_or_b32_sdwa v52, v52, v56 dst_sel:DWORD dst_unused:UNUSED_PAD src0_sel:DWORD src1_sel:WORD_1
	v_lshlrev_b32_e32 v57, 16, v55
	v_lshlrev_b32_e32 v56, 16, v54
	v_pk_mul_f32 v[56:57], v[60:61], v[56:57]
	v_and_b32_e32 v55, 0xffff0000, v55
	v_and_b32_e32 v54, 0xffff0000, v54
	v_pk_mul_f32 v[54:55], v[62:63], v[54:55]
	v_and_b32_sdwa v58, v57, v95 dst_sel:DWORD dst_unused:UNUSED_PAD src0_sel:WORD_1 src1_sel:DWORD
	v_and_b32_sdwa v59, v56, v95 dst_sel:DWORD dst_unused:UNUSED_PAD src0_sel:WORD_1 src1_sel:DWORD
	v_add3_u32 v56, v56, v59, s39
	v_add3_u32 v57, v57, v58, s39
	v_and_b32_sdwa v58, v55, v95 dst_sel:DWORD dst_unused:UNUSED_PAD src0_sel:WORD_1 src1_sel:DWORD
	v_and_b32_sdwa v59, v54, v95 dst_sel:DWORD dst_unused:UNUSED_PAD src0_sel:WORD_1 src1_sel:DWORD
	v_add3_u32 v55, v55, v58, s39
	v_add3_u32 v54, v54, v59, s39
	v_and_b32_e32 v55, 0xffff0000, v55
	v_and_b32_e32 v54, 0xffff0000, v54
	v_or_b32_sdwa v55, v55, v57 dst_sel:DWORD dst_unused:UNUSED_PAD src0_sel:DWORD src1_sel:WORD_1
	v_or_b32_sdwa v54, v54, v56 dst_sel:DWORD dst_unused:UNUSED_PAD src0_sel:DWORD src1_sel:WORD_1
	ds_write_b128 v112, v[52:55] offset:44032
	ds_read_b128 v[52:55], v111 offset:62752
	ds_read_b128 v[58:61], v111 offset:62768
	s_waitcnt lgkmcnt(1)
	v_mul_f32_e32 v52, 0x3fb8aa3b, v52
	v_exp_f32_e32 v62, v52
	v_mul_f32_e32 v52, 0x3fb8aa3b, v53
	v_exp_f32_e32 v56, v52
	v_mul_f32_e32 v52, 0x3fb8aa3b, v54
	v_exp_f32_e32 v63, v52
	v_mul_f32_e32 v52, 0x3fb8aa3b, v55
	v_exp_f32_e32 v57, v52
	s_waitcnt lgkmcnt(0)
	v_mul_f32_e32 v52, 0x3fb8aa3b, v58
	v_exp_f32_e32 v54, v52
	v_mul_f32_e32 v52, 0x3fb8aa3b, v59
	s_waitcnt vmcnt(0)
	v_lshlrev_b32_e32 v59, 16, v49
	v_lshlrev_b32_e32 v58, 16, v48
	v_pk_mul_f32 v[58:59], v[62:63], v[58:59]
	v_and_b32_e32 v49, 0xffff0000, v49
	v_and_b32_e32 v48, 0xffff0000, v48
	v_mul_f32_e32 v53, 0x3fb8aa3b, v60
	v_pk_mul_f32 v[48:49], v[56:57], v[48:49]
	v_and_b32_sdwa v56, v59, v95 dst_sel:DWORD dst_unused:UNUSED_PAD src0_sel:WORD_1 src1_sel:DWORD
	v_and_b32_sdwa v57, v58, v95 dst_sel:DWORD dst_unused:UNUSED_PAD src0_sel:WORD_1 src1_sel:DWORD
	v_exp_f32_e32 v55, v53
	v_mul_f32_e32 v53, 0x3fb8aa3b, v61
	v_add3_u32 v57, v58, v57, s39
	v_add3_u32 v56, v59, v56, s39
	v_and_b32_sdwa v58, v49, v95 dst_sel:DWORD dst_unused:UNUSED_PAD src0_sel:WORD_1 src1_sel:DWORD
	v_and_b32_sdwa v59, v48, v95 dst_sel:DWORD dst_unused:UNUSED_PAD src0_sel:WORD_1 src1_sel:DWORD
	v_exp_f32_e32 v52, v52
	v_exp_f32_e32 v53, v53
	v_add3_u32 v49, v49, v58, s39
	v_add3_u32 v48, v48, v59, s39
	v_and_b32_e32 v49, 0xffff0000, v49
	v_and_b32_e32 v48, 0xffff0000, v48
	v_or_b32_sdwa v49, v49, v56 dst_sel:DWORD dst_unused:UNUSED_PAD src0_sel:DWORD src1_sel:WORD_1
	v_or_b32_sdwa v48, v48, v57 dst_sel:DWORD dst_unused:UNUSED_PAD src0_sel:DWORD src1_sel:WORD_1
	v_lshlrev_b32_e32 v57, 16, v51
	v_lshlrev_b32_e32 v56, 16, v50
	v_pk_mul_f32 v[54:55], v[54:55], v[56:57]
	v_and_b32_e32 v51, 0xffff0000, v51
	v_and_b32_e32 v50, 0xffff0000, v50
	v_pk_mul_f32 v[50:51], v[52:53], v[50:51]
	v_and_b32_sdwa v52, v55, v95 dst_sel:DWORD dst_unused:UNUSED_PAD src0_sel:WORD_1 src1_sel:DWORD
	v_and_b32_sdwa v53, v54, v95 dst_sel:DWORD dst_unused:UNUSED_PAD src0_sel:WORD_1 src1_sel:DWORD
	v_add3_u32 v53, v54, v53, s39
	v_add3_u32 v52, v55, v52, s39
	v_and_b32_sdwa v54, v51, v95 dst_sel:DWORD dst_unused:UNUSED_PAD src0_sel:WORD_1 src1_sel:DWORD
	v_and_b32_sdwa v55, v50, v95 dst_sel:DWORD dst_unused:UNUSED_PAD src0_sel:WORD_1 src1_sel:DWORD
	v_add3_u32 v51, v51, v54, s39
	v_add3_u32 v50, v50, v55, s39
	v_and_b32_e32 v51, 0xffff0000, v51
	v_and_b32_e32 v50, 0xffff0000, v50
	v_or_b32_sdwa v51, v51, v52 dst_sel:DWORD dst_unused:UNUSED_PAD src0_sel:DWORD src1_sel:WORD_1
	v_or_b32_sdwa v50, v50, v53 dst_sel:DWORD dst_unused:UNUSED_PAD src0_sel:DWORD src1_sel:WORD_1
	ds_write_b128 v112, v[48:51] offset:44048
	ds_read_b128 v[48:51], v111 offset:62784
	ds_read_b128 v[52:55], v111 offset:62800
	s_waitcnt lgkmcnt(1)
; DEVI void h3_item(const Params& P, int l, int ck, int h, char* smem, int tid) {
;     ...
; #pragma unroll
;       for (int q4 = 0; q4 < 4; ++q4) {
;         uint4 v = *reinterpret_cast<const uint4*>(src + e2 * 128 + sl * 64 + dd0 + q4 * 8);
;         const float* bm = bmid + sl * 64 + dd0 + q4 * 8;
;         unsigned vv[4] = {v.x, v.y, v.z, v.w};
;         unsigned rr[4];
; #pragma unroll
;         for (int i = 0; i < 4; ++i) {
;           float lo = __uint_as_float(vv[i] << 16) * __expf(bm[2 * i]);
;           float hi = __uint_as_float(vv[i] & 0xFFFF0000u) * __expf(bm[2 * i + 1]);
;           rr[i] = f2b(lo) | ((unsigned)f2b(hi) << 16);
;         }
;         *reinterpret_cast<uint4*>(BS + e2 * 72 + dd0 + q4 * 8) = make_uint4(rr[0], rr[1], rr[2], rr[3]);
;       }
	v_mul_f32_e32 v49, 0x3fb8aa3b, v49
	v_mul_f32_e32 v48, 0x3fb8aa3b, v48
	v_exp_f32_e32 v56, v49
	v_mul_f32_e32 v49, 0x3fb8aa3b, v50
	v_exp_f32_e32 v48, v48
	v_exp_f32_e32 v49, v49
	v_mul_f32_e32 v50, 0x3fb8aa3b, v51
	v_exp_f32_e32 v57, v50
	s_waitcnt lgkmcnt(0)
	v_mul_f32_e32 v51, 0x3fb8aa3b, v53
	v_mul_f32_e32 v50, 0x3fb8aa3b, v52
	v_exp_f32_e32 v52, v51
	v_mul_f32_e32 v51, 0x3fb8aa3b, v54
	v_mul_f32_e32 v53, 0x3fb8aa3b, v55
	v_lshlrev_b32_e32 v55, 16, v45
	v_lshlrev_b32_e32 v54, 16, v44
	v_pk_mul_f32 v[48:49], v[48:49], v[54:55]
	v_and_b32_e32 v45, 0xffff0000, v45
	v_and_b32_e32 v44, 0xffff0000, v44
	v_pk_mul_f32 v[44:45], v[56:57], v[44:45]
	v_and_b32_sdwa v54, v49, v95 dst_sel:DWORD dst_unused:UNUSED_PAD src0_sel:WORD_1 src1_sel:DWORD
	v_and_b32_sdwa v55, v48, v95 dst_sel:DWORD dst_unused:UNUSED_PAD src0_sel:WORD_1 src1_sel:DWORD
	v_exp_f32_e32 v50, v50
	v_exp_f32_e32 v51, v51
	v_add3_u32 v48, v48, v55, s39
	v_add3_u32 v49, v49, v54, s39
	v_and_b32_sdwa v54, v45, v95 dst_sel:DWORD dst_unused:UNUSED_PAD src0_sel:WORD_1 src1_sel:DWORD
	v_and_b32_sdwa v55, v44, v95 dst_sel:DWORD dst_unused:UNUSED_PAD src0_sel:WORD_1 src1_sel:DWORD
	v_exp_f32_e32 v53, v53
	v_add3_u32 v45, v45, v54, s39
	v_add3_u32 v44, v44, v55, s39
	v_and_b32_e32 v45, 0xffff0000, v45
	v_and_b32_e32 v44, 0xffff0000, v44
	v_or_b32_sdwa v45, v45, v49 dst_sel:DWORD dst_unused:UNUSED_PAD src0_sel:DWORD src1_sel:WORD_1
	v_or_b32_sdwa v44, v44, v48 dst_sel:DWORD dst_unused:UNUSED_PAD src0_sel:DWORD src1_sel:WORD_1
	v_lshlrev_b32_e32 v49, 16, v47
	v_lshlrev_b32_e32 v48, 16, v46
	v_pk_mul_f32 v[48:49], v[50:51], v[48:49]
	v_and_b32_e32 v47, 0xffff0000, v47
	v_and_b32_e32 v46, 0xffff0000, v46
	v_pk_mul_f32 v[46:47], v[52:53], v[46:47]
	v_and_b32_sdwa v50, v49, v95 dst_sel:DWORD dst_unused:UNUSED_PAD src0_sel:WORD_1 src1_sel:DWORD
	v_and_b32_sdwa v51, v48, v95 dst_sel:DWORD dst_unused:UNUSED_PAD src0_sel:WORD_1 src1_sel:DWORD
	v_add3_u32 v48, v48, v51, s39
	v_add3_u32 v49, v49, v50, s39
	v_and_b32_sdwa v50, v47, v95 dst_sel:DWORD dst_unused:UNUSED_PAD src0_sel:WORD_1 src1_sel:DWORD
	v_and_b32_sdwa v51, v46, v95 dst_sel:DWORD dst_unused:UNUSED_PAD src0_sel:WORD_1 src1_sel:DWORD
	v_add3_u32 v47, v47, v50, s39
	v_add3_u32 v46, v46, v51, s39
	v_and_b32_e32 v47, 0xffff0000, v47
	v_and_b32_e32 v46, 0xffff0000, v46
	v_or_b32_sdwa v47, v47, v49 dst_sel:DWORD dst_unused:UNUSED_PAD src0_sel:DWORD src1_sel:WORD_1
	v_or_b32_sdwa v46, v46, v48 dst_sel:DWORD dst_unused:UNUSED_PAD src0_sel:DWORD src1_sel:WORD_1
	ds_write_b128 v112, v[44:47] offset:44064
	ds_read_b128 v[44:47], v111 offset:62816
	ds_read_b128 v[48:51], v111 offset:62832
	s_waitcnt lgkmcnt(1)
	v_mul_f32_e32 v45, 0x3fb8aa3b, v45
	v_mul_f32_e32 v44, 0x3fb8aa3b, v44
	v_exp_f32_e32 v52, v45
	v_mul_f32_e32 v45, 0x3fb8aa3b, v46
	v_exp_f32_e32 v44, v44
	v_exp_f32_e32 v45, v45
	v_mul_f32_e32 v46, 0x3fb8aa3b, v47
	v_exp_f32_e32 v53, v46
	s_waitcnt lgkmcnt(0)
	v_mul_f32_e32 v47, 0x3fb8aa3b, v49
	v_mul_f32_e32 v46, 0x3fb8aa3b, v48
	v_exp_f32_e32 v48, v47
	v_mul_f32_e32 v47, 0x3fb8aa3b, v50
	v_mul_f32_e32 v49, 0x3fb8aa3b, v51
	v_lshlrev_b32_e32 v51, 16, v41
	v_lshlrev_b32_e32 v50, 16, v40
	v_pk_mul_f32 v[44:45], v[44:45], v[50:51]
	v_and_b32_e32 v41, 0xffff0000, v41
	v_and_b32_e32 v40, 0xffff0000, v40
	v_pk_mul_f32 v[40:41], v[52:53], v[40:41]
	v_and_b32_sdwa v50, v45, v95 dst_sel:DWORD dst_unused:UNUSED_PAD src0_sel:WORD_1 src1_sel:DWORD
	v_and_b32_sdwa v51, v44, v95 dst_sel:DWORD dst_unused:UNUSED_PAD src0_sel:WORD_1 src1_sel:DWORD
	v_exp_f32_e32 v46, v46
	v_exp_f32_e32 v47, v47
	v_add3_u32 v44, v44, v51, s39
	v_add3_u32 v45, v45, v50, s39
	v_and_b32_sdwa v50, v41, v95 dst_sel:DWORD dst_unused:UNUSED_PAD src0_sel:WORD_1 src1_sel:DWORD
	v_and_b32_sdwa v51, v40, v95 dst_sel:DWORD dst_unused:UNUSED_PAD src0_sel:WORD_1 src1_sel:DWORD
	v_exp_f32_e32 v49, v49
	v_add3_u32 v41, v41, v50, s39
	v_add3_u32 v40, v40, v51, s39
	v_and_b32_e32 v41, 0xffff0000, v41
	v_and_b32_e32 v40, 0xffff0000, v40
	v_or_b32_sdwa v41, v41, v45 dst_sel:DWORD dst_unused:UNUSED_PAD src0_sel:DWORD src1_sel:WORD_1
	v_or_b32_sdwa v40, v40, v44 dst_sel:DWORD dst_unused:UNUSED_PAD src0_sel:DWORD src1_sel:WORD_1
	v_lshlrev_b32_e32 v45, 16, v43
	v_lshlrev_b32_e32 v44, 16, v42
	v_pk_mul_f32 v[44:45], v[46:47], v[44:45]
	v_and_b32_e32 v43, 0xffff0000, v43
	v_and_b32_e32 v42, 0xffff0000, v42
	v_pk_mul_f32 v[42:43], v[48:49], v[42:43]
	v_and_b32_sdwa v46, v45, v95 dst_sel:DWORD dst_unused:UNUSED_PAD src0_sel:WORD_1 src1_sel:DWORD
	v_and_b32_sdwa v47, v44, v95 dst_sel:DWORD dst_unused:UNUSED_PAD src0_sel:WORD_1 src1_sel:DWORD
	v_add3_u32 v44, v44, v47, s39
	v_add3_u32 v45, v45, v46, s39
	v_and_b32_sdwa v46, v43, v95 dst_sel:DWORD dst_unused:UNUSED_PAD src0_sel:WORD_1 src1_sel:DWORD
	v_and_b32_sdwa v47, v42, v95 dst_sel:DWORD dst_unused:UNUSED_PAD src0_sel:WORD_1 src1_sel:DWORD
	v_add3_u32 v43, v43, v46, s39
	v_add3_u32 v42, v42, v47, s39
	v_and_b32_e32 v43, 0xffff0000, v43
	v_and_b32_e32 v42, 0xffff0000, v42
	v_or_b32_sdwa v43, v43, v45 dst_sel:DWORD dst_unused:UNUSED_PAD src0_sel:DWORD src1_sel:WORD_1
	v_or_b32_sdwa v42, v42, v44 dst_sel:DWORD dst_unused:UNUSED_PAD src0_sel:DWORD src1_sel:WORD_1
	ds_write_b128 v112, v[40:43] offset:44080
